# GEMM K-loop heads and the attention tile-loop head aligned to 64 bytes
# speedup vs baseline: 1.0035x; 1.0009x over previous
.Lattn_slc:
	s_mov_b64 exec, -1
	s_waitcnt vmcnt(0) lgkmcnt(0)
	v_lshrrev_b32_e32 v0, 6, v162
	s_nop 0
	v_readfirstlane_b32 s49, v0
	v_readlane_b32 s58, v255, 5
	v_readlane_b32 s59, v255, 6
	v_readlane_b32 s60, v255, 7
	v_readlane_b32 s61, v255, 8
	v_readlane_b32 s62, v254, 49
	v_readlane_b32 s63, v255, 0
	s_lshl_b32 s40, s49, 10
	s_add_i32 s41, s40, 0x8000
	s_add_i32 s48, s36, -1
	s_mov_b32 s43, 0
	s_mov_b32 s45, 0
	s_mov_b32 s38, 0
	v_and_b32_e32 v0, 31, v210
	v_lshrrev_b32_e32 v252, 5, v210
	v_bfe_u32 v248, v0, 1, 1
	v_xor_b32_e32 v248, v252, v248
	v_and_b32_e32 v249, 0x13, v0
	v_bfe_u32 v250, v0, 2, 1
	v_bfe_u32 v251, v0, 3, 1
	v_lshl_or_b32 v249, v250, 3, v249
	v_lshl_or_b32 v249, v251, 2, v249
	v_lshlrev_b32_e32 v249, 7, v249
	v_lshl_add_u32 v249, v248, 4, v249
	v_bfe_u32 v251, v0, 4, 1
	v_lshl_or_b32 v250, v251, 1, v250
	v_xor_b32_e32 v40, 0, v250
	v_lshl_add_u32 v40, v40, 5, v249
	v_xor_b32_e32 v41, 1, v250
	v_lshl_add_u32 v41, v41, 5, v249
	v_xor_b32_e32 v42, 2, v250
	v_lshl_add_u32 v42, v42, 5, v249
	v_xor_b32_e32 v96, 3, v250
	v_lshl_add_u32 v96, v96, 5, v249
	v_lshlrev_b32_e32 v249, 7, v0
	v_lshl_add_u32 v249, v248, 4, v249
	v_bfe_u32 v250, v0, 2, 2
	v_xor_b32_e32 v97, 0, v250
	v_lshl_add_u32 v97, v97, 5, v249
	v_xor_b32_e32 v98, 1, v250
	v_lshl_add_u32 v98, v98, 5, v249
	v_xor_b32_e32 v102, 2, v250
	v_lshl_add_u32 v102, v102, 5, v249
	v_xor_b32_e32 v103, 3, v250
	v_lshl_add_u32 v103, v103, 5, v249
	v_mov_b32_e32 v198, v20
	v_mov_b32_e32 v199, v21
	v_mov_b32_e32 v250, v22
	v_mov_b32_e32 v251, v23
	v_lshrrev_b32_e32 v0, 3, v210
	v_and_b32_e32 v248, 7, v210
	v_bfe_u32 v249, v210, 4, 1
	s_and_b32 s50, s49, 3
	s_lshl_b32 s50, s50, 1
	v_or_b32_e32 v249, s50, v249
	v_xor_b32_e32 v249, v248, v249
	s_lshl_b32 s51, s49, 11
	v_lshl_add_u32 v208, v0, 8, s51
	v_lshl_add_u32 v208, v249, 4, v208
	v_mov_b32_e32 v209, 0
	v_lshl_add_u64 v[106:107], s[58:59], 0, v[208:209]
	v_bfe_u32 v249, v210, 4, 2
	s_and_b32 s50, s49, 1
	s_lshl_b32 s50, s50, 2
	v_or_b32_e32 v249, s50, v249
	v_xor_b32_e32 v249, v248, v249
	s_lshl_b32 s51, s49, 17
	v_lshl_add_u32 v208, v0, 14, s51
	v_lshl_add_u32 v208, v249, 4, v208
	v_lshl_add_u64 v[122:123], s[60:61], 0, v[208:209]
	v_add_u32_e32 v160, s62, v172
	v_mov_b32_e32 v161, 0
	v_lshlrev_b64 v[160:161], 10, v[160:161]
	v_lshl_add_u64 v[160:161], v[160:161], 0, s[86:87]
	v_bfe_u32 v208, v210, 4, 1
	v_lshlrev_b32_e32 v208, 6, v208
	v_lshl_add_u32 v208, v252, 3, v208
	v_add_u32_e32 v208, s63, v208
	v_lshlrev_b32_e32 v208, 1, v208
	v_lshl_add_u64 v[160:161], v[208:209], 0, v[160:161]
	global_load_dwordx4 v[4:7], v[160:161], off
	global_load_dwordx4 v[8:11], v[160:161], off offset:32
	global_load_dwordx4 v[12:15], v[160:161], off offset:64
	global_load_dwordx4 v[16:19], v[160:161], off offset:96
	v_cmp_eq_u32_e64 s[50:51], 0, v252
	v_xor_b32_e32 v0, 0x80000000, v227
	v_cvt_pk_bf16_f32 v129, v0, 0
	v_cvt_pk_bf16_f32 v171, v197, 0
	v_mov_b32_e32 v0, 0x3f80
	v_cndmask_b32_e64 v129, 0, v129, s[50:51]
	v_cndmask_b32_e64 v171, 0, v171, s[50:51]
	v_cndmask_b32_e64 v204, 0, v0, s[50:51]
	v_mov_b32_e32 v205, 0
	v_mov_b32_e32 v245, 0
	v_mov_b32_e32 v206, 0
	v_mov_b32_e32 v246, 0
	v_mov_b32_e32 v207, 0
	v_mov_b32_e32 v247, 0
	s_lshl_b32 s50, s48, 6
	v_subrev_u32_e32 v120, s50, v172
	v_lshlrev_b32_e32 v0, 3, v252
	v_sub_u32_e32 v120, v120, v0
	v_mov_b32_e32 v176, 0
	v_mov_b32_e32 v177, 0
	v_mov_b32_e32 v178, 0
	v_mov_b32_e32 v179, 0
	v_mov_b32_e32 v180, 0
	v_mov_b32_e32 v181, 0
	v_mov_b32_e32 v182, 0
	v_mov_b32_e32 v183, 0
	v_mov_b32_e32 v184, 0
	v_mov_b32_e32 v185, 0
	v_mov_b32_e32 v186, 0
	v_mov_b32_e32 v187, 0
	v_mov_b32_e32 v188, 0
	v_mov_b32_e32 v189, 0
	v_mov_b32_e32 v190, 0
	v_mov_b32_e32 v191, 0
	v_mov_b32_e32 v228, 0
	v_mov_b32_e32 v229, 0
	v_mov_b32_e32 v230, 0
	v_mov_b32_e32 v231, 0
	v_mov_b32_e32 v232, 0
	v_mov_b32_e32 v233, 0
	v_mov_b32_e32 v234, 0
	v_mov_b32_e32 v235, 0
	v_mov_b32_e32 v236, 0
	v_mov_b32_e32 v237, 0
	v_mov_b32_e32 v238, 0
	v_mov_b32_e32 v239, 0
	v_mov_b32_e32 v240, 0
	v_mov_b32_e32 v241, 0
	v_mov_b32_e32 v242, 0
	v_mov_b32_e32 v243, 0
	v_mov_b32_e32 v68, 0
	v_mov_b32_e32 v69, 0
	v_mov_b32_e32 v70, 0
	v_mov_b32_e32 v71, 0
	v_mov_b32_e32 v72, 0
	v_mov_b32_e32 v73, 0
	v_mov_b32_e32 v74, 0
	v_mov_b32_e32 v75, 0
	v_mov_b32_e32 v76, 0
	v_mov_b32_e32 v77, 0
	v_mov_b32_e32 v78, 0
	v_mov_b32_e32 v79, 0
	v_mov_b32_e32 v80, 0
	v_mov_b32_e32 v81, 0
	v_mov_b32_e32 v82, 0
	v_mov_b32_e32 v83, 0
	v_mov_b32_e32 v132, 0
	v_mov_b32_e32 v133, 0
	v_mov_b32_e32 v134, 0
	v_mov_b32_e32 v135, 0
	v_mov_b32_e32 v136, 0
	v_mov_b32_e32 v137, 0
	v_mov_b32_e32 v138, 0
	v_mov_b32_e32 v139, 0
	v_mov_b32_e32 v140, 0
	v_mov_b32_e32 v141, 0
	v_mov_b32_e32 v142, 0
	v_mov_b32_e32 v143, 0
	v_mov_b32_e32 v144, 0
	v_mov_b32_e32 v145, 0
	v_mov_b32_e32 v146, 0
	v_mov_b32_e32 v147, 0
	v_mov_b32_e32 v174, 0
	v_mov_b32_e32 v193, 0
	v_and_b32_e32 v248, 1, v198
	v_cmp_eq_u32_e64 s[50:51], 1, v248
	s_nop 1
	v_cndmask_b32_e64 v244, v171, v129, s[50:51]
	s_waitcnt vmcnt(0)
	s_min_u32 s46, s48, 0
	s_lshl_b32 s42, s46, 14
	v_lshl_add_u64 v[160:161], s[42:43], 0, v[106:107]
	s_add_i32 m0, s40, 0x0
	s_nop 0
	global_load_lds_dwordx4 v[160:161], off
	s_min_u32 s46, s48, 1
	s_lshl_b32 s42, s46, 14
	v_lshl_add_u64 v[160:161], s[42:43], 0, v[106:107]
	s_add_i32 m0, s40, 0x2000
	s_nop 0
	global_load_lds_dwordx4 v[160:161], off
	s_min_u32 s47, s48, 0
	s_lshl_b32 s44, s47, 7
	v_lshl_add_u64 v[208:209], s[44:45], 0, v[122:123]
	s_add_i32 m0, s41, 0x6000
	s_nop 0
	global_load_lds_dwordx4 v[208:209], off
	s_min_u32 s46, s48, 2
	s_lshl_b32 s42, s46, 14
	v_lshl_add_u64 v[160:161], s[42:43], 0, v[106:107]
	s_add_i32 m0, s40, 0x4000
	s_nop 0
	global_load_lds_dwordx4 v[160:161], off
	s_min_u32 s47, s48, 0
	s_lshl_b32 s44, s47, 7
	v_lshl_add_u64 v[208:209], s[44:45], 0, v[122:123]
	s_add_i32 m0, s41, 0x0
	s_nop 0
	global_load_lds_dwordx4 v[208:209], off
	s_min_u32 s46, s48, 3
	s_lshl_b32 s42, s46, 14
	v_lshl_add_u64 v[160:161], s[42:43], 0, v[106:107]
	s_add_i32 m0, s40, 0x6000
	s_nop 0
	global_load_lds_dwordx4 v[160:161], off
	s_min_u32 s47, s48, 1
	s_lshl_b32 s44, s47, 7
	v_lshl_add_u64 v[208:209], s[44:45], 0, v[122:123]
	s_add_i32 m0, s41, 0x2000
	s_nop 0
	global_load_lds_dwordx4 v[208:209], off
	s_waitcnt vmcnt(6)
	s_barrier
	ds_read_b128 v[108:111], v40 offset:0
	ds_read_b128 v[112:115], v41 offset:0
	ds_read_b128 v[116:119], v42 offset:0
	ds_read_b128 v[124:127], v96 offset:0
	ds_read_b128 v[148:151], v40 offset:4096
	ds_read_b128 v[152:155], v41 offset:4096
	ds_read_b128 v[156:159], v42 offset:4096
	ds_read_b128 v[200:203], v96 offset:4096
	.p2align	6

.LBB0_627:
	s_ashr_i32 s15, s14, 31
	s_lshl_b64 s[16:17], s[14:15], 19
	s_add_u32 s16, s28, s16
	s_addc_u32 s17, s29, s17
	s_and_b64 s[18:19], s[34:35], exec
	s_cselect_b32 s15, s17, s31
	s_cselect_b32 s48, s16, s30
	s_ashr_i32 s13, s12, 31
	s_lshl_b64 s[18:19], s[12:13], 19
	s_add_u32 s18, s6, s18
	s_addc_u32 s19, s7, s19
	s_and_b64 s[38:39], s[34:35], exec
	s_cselect_b32 s13, s19, s37
	s_cselect_b32 s49, s18, s36
	s_add_u32 s30, s30, 0x40080
	s_addc_u32 s31, s31, 0
	s_add_u32 s50, s36, 0x100
	v_mov_b32_e32 v2, 0
	s_addc_u32 s51, s37, 0
	s_mov_b32 s52, -2
	v_mov_b32_e32 v3, v2
	v_pk_mov_b32 v[4:5], v[2:3], v[2:3]
	v_pk_mov_b32 v[6:7], v[2:3], v[2:3]
	v_pk_mov_b32 v[8:9], v[2:3], v[2:3]
	v_pk_mov_b32 v[10:11], v[2:3], v[2:3]
	v_pk_mov_b32 v[12:13], v[2:3], v[2:3]
	v_pk_mov_b32 v[14:15], v[2:3], v[2:3]
	v_pk_mov_b32 v[16:17], v[2:3], v[2:3]
	v_pk_mov_b32 v[18:19], v[2:3], v[2:3]
	v_pk_mov_b32 v[20:21], v[2:3], v[2:3]
	v_pk_mov_b32 v[22:23], v[2:3], v[2:3]
	v_pk_mov_b32 v[24:25], v[2:3], v[2:3]
	v_pk_mov_b32 v[26:27], v[2:3], v[2:3]
	v_pk_mov_b32 v[28:29], v[2:3], v[2:3]
	v_pk_mov_b32 v[30:31], v[2:3], v[2:3]
	v_pk_mov_b32 v[32:33], v[2:3], v[2:3]
	v_pk_mov_b32 v[34:35], v[2:3], v[2:3]
	v_pk_mov_b32 v[36:37], v[2:3], v[2:3]
	v_pk_mov_b32 v[38:39], v[2:3], v[2:3]
	v_pk_mov_b32 v[40:41], v[2:3], v[2:3]
	v_pk_mov_b32 v[42:43], v[2:3], v[2:3]
	v_pk_mov_b32 v[44:45], v[2:3], v[2:3]
	v_pk_mov_b32 v[46:47], v[2:3], v[2:3]
	v_pk_mov_b32 v[48:49], v[2:3], v[2:3]
	v_pk_mov_b32 v[50:51], v[2:3], v[2:3]
	v_pk_mov_b32 v[52:53], v[2:3], v[2:3]
	v_pk_mov_b32 v[54:55], v[2:3], v[2:3]
	v_pk_mov_b32 v[56:57], v[2:3], v[2:3]
	v_pk_mov_b32 v[58:59], v[2:3], v[2:3]
	v_pk_mov_b32 v[60:61], v[2:3], v[2:3]
	v_pk_mov_b32 v[62:63], v[2:3], v[2:3]
	v_pk_mov_b32 v[64:65], v[2:3], v[2:3]
	v_pk_mov_b32 v[66:67], v[2:3], v[2:3]
	v_pk_mov_b32 v[68:69], v[2:3], v[2:3]
	v_pk_mov_b32 v[70:71], v[2:3], v[2:3]
	v_pk_mov_b32 v[72:73], v[2:3], v[2:3]
	v_pk_mov_b32 v[74:75], v[2:3], v[2:3]
	v_pk_mov_b32 v[76:77], v[2:3], v[2:3]
	v_pk_mov_b32 v[78:79], v[2:3], v[2:3]
	v_pk_mov_b32 v[80:81], v[2:3], v[2:3]
	v_pk_mov_b32 v[82:83], v[2:3], v[2:3]
	v_pk_mov_b32 v[84:85], v[2:3], v[2:3]
	v_pk_mov_b32 v[86:87], v[2:3], v[2:3]
	v_pk_mov_b32 v[88:89], v[2:3], v[2:3]
	v_pk_mov_b32 v[90:91], v[2:3], v[2:3]
	v_pk_mov_b32 v[92:93], v[2:3], v[2:3]
	v_pk_mov_b32 v[94:95], v[2:3], v[2:3]
	v_pk_mov_b32 v[96:97], v[2:3], v[2:3]
	v_pk_mov_b32 v[98:99], v[2:3], v[2:3]
	v_pk_mov_b32 v[100:101], v[2:3], v[2:3]
	v_pk_mov_b32 v[102:103], v[2:3], v[2:3]
	v_pk_mov_b32 v[104:105], v[2:3], v[2:3]
	v_pk_mov_b32 v[106:107], v[2:3], v[2:3]
	v_pk_mov_b32 v[108:109], v[2:3], v[2:3]
	v_pk_mov_b32 v[110:111], v[2:3], v[2:3]
	v_pk_mov_b32 v[112:113], v[2:3], v[2:3]
	v_pk_mov_b32 v[114:115], v[2:3], v[2:3]
	v_pk_mov_b32 v[116:117], v[2:3], v[2:3]
	v_pk_mov_b32 v[118:119], v[2:3], v[2:3]
	v_pk_mov_b32 v[120:121], v[2:3], v[2:3]
	v_pk_mov_b32 v[122:123], v[2:3], v[2:3]
	v_pk_mov_b32 v[124:125], v[2:3], v[2:3]
	v_pk_mov_b32 v[126:127], v[2:3], v[2:3]
	v_pk_mov_b32 v[128:129], v[2:3], v[2:3]
	.p2align	6

.LBB0_681:
	s_add_u32 s12, s12, 0x80
	s_addc_u32 s13, s13, 0
	s_add_u32 s40, s40, 0x100
	v_mov_b32_e32 v2, 0
	s_addc_u32 s41, s41, 0
	s_mov_b32 s38, 0
	v_mov_b32_e32 v3, v2
	v_pk_mov_b32 v[4:5], v[2:3], v[2:3]
	v_pk_mov_b32 v[6:7], v[2:3], v[2:3]
	v_pk_mov_b32 v[8:9], v[2:3], v[2:3]
	v_pk_mov_b32 v[10:11], v[2:3], v[2:3]
	v_pk_mov_b32 v[12:13], v[2:3], v[2:3]
	v_pk_mov_b32 v[14:15], v[2:3], v[2:3]
	v_pk_mov_b32 v[16:17], v[2:3], v[2:3]
	v_pk_mov_b32 v[18:19], v[2:3], v[2:3]
	v_pk_mov_b32 v[20:21], v[2:3], v[2:3]
	v_pk_mov_b32 v[22:23], v[2:3], v[2:3]
	v_pk_mov_b32 v[24:25], v[2:3], v[2:3]
	v_pk_mov_b32 v[26:27], v[2:3], v[2:3]
	v_pk_mov_b32 v[28:29], v[2:3], v[2:3]
	v_pk_mov_b32 v[30:31], v[2:3], v[2:3]
	v_pk_mov_b32 v[32:33], v[2:3], v[2:3]
	v_pk_mov_b32 v[34:35], v[2:3], v[2:3]
	v_pk_mov_b32 v[36:37], v[2:3], v[2:3]
	v_pk_mov_b32 v[42:43], v[2:3], v[2:3]
	v_pk_mov_b32 v[44:45], v[2:3], v[2:3]
	v_pk_mov_b32 v[58:59], v[2:3], v[2:3]
	v_pk_mov_b32 v[60:61], v[2:3], v[2:3]
	v_pk_mov_b32 v[62:63], v[2:3], v[2:3]
	v_pk_mov_b32 v[64:65], v[2:3], v[2:3]
	v_pk_mov_b32 v[66:67], v[2:3], v[2:3]
	v_pk_mov_b32 v[68:69], v[2:3], v[2:3]
	v_pk_mov_b32 v[70:71], v[2:3], v[2:3]
	v_pk_mov_b32 v[72:73], v[2:3], v[2:3]
	v_pk_mov_b32 v[74:75], v[2:3], v[2:3]
	v_pk_mov_b32 v[76:77], v[2:3], v[2:3]
	v_pk_mov_b32 v[78:79], v[2:3], v[2:3]
	v_pk_mov_b32 v[80:81], v[2:3], v[2:3]
	v_pk_mov_b32 v[82:83], v[2:3], v[2:3]
	v_pk_mov_b32 v[84:85], v[2:3], v[2:3]
	v_pk_mov_b32 v[86:87], v[2:3], v[2:3]
	v_pk_mov_b32 v[88:89], v[2:3], v[2:3]
	v_pk_mov_b32 v[90:91], v[2:3], v[2:3]
	v_pk_mov_b32 v[92:93], v[2:3], v[2:3]
	v_pk_mov_b32 v[94:95], v[2:3], v[2:3]
	v_pk_mov_b32 v[96:97], v[2:3], v[2:3]
	v_pk_mov_b32 v[98:99], v[2:3], v[2:3]
	v_pk_mov_b32 v[100:101], v[2:3], v[2:3]
	v_pk_mov_b32 v[102:103], v[2:3], v[2:3]
	v_pk_mov_b32 v[104:105], v[2:3], v[2:3]
	v_pk_mov_b32 v[106:107], v[2:3], v[2:3]
	v_pk_mov_b32 v[108:109], v[2:3], v[2:3]
	v_pk_mov_b32 v[110:111], v[2:3], v[2:3]
	v_pk_mov_b32 v[112:113], v[2:3], v[2:3]
	v_pk_mov_b32 v[114:115], v[2:3], v[2:3]
	v_pk_mov_b32 v[116:117], v[2:3], v[2:3]
	v_pk_mov_b32 v[118:119], v[2:3], v[2:3]
	v_pk_mov_b32 v[120:121], v[2:3], v[2:3]
	v_pk_mov_b32 v[122:123], v[2:3], v[2:3]
	v_pk_mov_b32 v[124:125], v[2:3], v[2:3]
	v_pk_mov_b32 v[126:127], v[2:3], v[2:3]
	v_pk_mov_b32 v[128:129], v[2:3], v[2:3]
	v_pk_mov_b32 v[130:131], v[2:3], v[2:3]
	v_pk_mov_b32 v[132:133], v[2:3], v[2:3]
	v_pk_mov_b32 v[134:135], v[2:3], v[2:3]
	v_pk_mov_b32 v[136:137], v[2:3], v[2:3]
	v_pk_mov_b32 v[138:139], v[2:3], v[2:3]
	v_pk_mov_b32 v[140:141], v[2:3], v[2:3]
	v_pk_mov_b32 v[142:143], v[2:3], v[2:3]
	v_pk_mov_b32 v[144:145], v[2:3], v[2:3]
	.p2align	6

.LBB0_811:
	s_ashr_i32 s17, s16, 31
	s_lshl_b64 s[18:19], s[16:17], 19
	s_add_u32 s18, s28, s18
	s_addc_u32 s19, s29, s19
	s_and_b64 s[26:27], s[34:35], exec
	s_cselect_b32 s17, s19, s37
	s_cselect_b32 s50, s18, s36
	s_ashr_i32 s15, s14, 31
	s_lshl_b64 s[26:27], s[14:15], 19
	s_add_u32 s26, s0, s26
	s_addc_u32 s27, s6, s27
	s_and_b64 s[40:41], s[34:35], exec
	s_cselect_b32 s15, s27, s39
	s_cselect_b32 s51, s26, s38
	s_add_u32 s36, s36, 0x40080
	s_addc_u32 s37, s37, 0
	s_add_u32 s52, s38, 0x100
	v_mov_b32_e32 v2, 0
	s_addc_u32 s53, s39, 0
	s_mov_b32 s54, -2
	v_mov_b32_e32 v3, v2
	v_pk_mov_b32 v[4:5], v[2:3], v[2:3]
	v_pk_mov_b32 v[6:7], v[2:3], v[2:3]
	v_pk_mov_b32 v[8:9], v[2:3], v[2:3]
	v_pk_mov_b32 v[10:11], v[2:3], v[2:3]
	v_pk_mov_b32 v[12:13], v[2:3], v[2:3]
	v_pk_mov_b32 v[14:15], v[2:3], v[2:3]
	v_pk_mov_b32 v[16:17], v[2:3], v[2:3]
	v_pk_mov_b32 v[18:19], v[2:3], v[2:3]
	v_pk_mov_b32 v[20:21], v[2:3], v[2:3]
	v_pk_mov_b32 v[22:23], v[2:3], v[2:3]
	v_pk_mov_b32 v[24:25], v[2:3], v[2:3]
	v_pk_mov_b32 v[26:27], v[2:3], v[2:3]
	v_pk_mov_b32 v[28:29], v[2:3], v[2:3]
	v_pk_mov_b32 v[30:31], v[2:3], v[2:3]
	v_pk_mov_b32 v[32:33], v[2:3], v[2:3]
	v_pk_mov_b32 v[34:35], v[2:3], v[2:3]
	v_pk_mov_b32 v[36:37], v[2:3], v[2:3]
	v_pk_mov_b32 v[38:39], v[2:3], v[2:3]
	v_pk_mov_b32 v[40:41], v[2:3], v[2:3]
	v_pk_mov_b32 v[42:43], v[2:3], v[2:3]
	v_pk_mov_b32 v[44:45], v[2:3], v[2:3]
	v_pk_mov_b32 v[46:47], v[2:3], v[2:3]
	v_pk_mov_b32 v[48:49], v[2:3], v[2:3]
	v_pk_mov_b32 v[50:51], v[2:3], v[2:3]
	v_pk_mov_b32 v[52:53], v[2:3], v[2:3]
	v_pk_mov_b32 v[54:55], v[2:3], v[2:3]
	v_pk_mov_b32 v[56:57], v[2:3], v[2:3]
	v_pk_mov_b32 v[58:59], v[2:3], v[2:3]
	v_pk_mov_b32 v[60:61], v[2:3], v[2:3]
	v_pk_mov_b32 v[62:63], v[2:3], v[2:3]
	v_pk_mov_b32 v[64:65], v[2:3], v[2:3]
	v_pk_mov_b32 v[66:67], v[2:3], v[2:3]
	v_pk_mov_b32 v[68:69], v[2:3], v[2:3]
	v_pk_mov_b32 v[70:71], v[2:3], v[2:3]
	v_pk_mov_b32 v[72:73], v[2:3], v[2:3]
	v_pk_mov_b32 v[74:75], v[2:3], v[2:3]
	v_pk_mov_b32 v[76:77], v[2:3], v[2:3]
	v_pk_mov_b32 v[78:79], v[2:3], v[2:3]
	v_pk_mov_b32 v[80:81], v[2:3], v[2:3]
	v_pk_mov_b32 v[82:83], v[2:3], v[2:3]
	v_pk_mov_b32 v[84:85], v[2:3], v[2:3]
	v_pk_mov_b32 v[86:87], v[2:3], v[2:3]
	v_pk_mov_b32 v[88:89], v[2:3], v[2:3]
	v_pk_mov_b32 v[90:91], v[2:3], v[2:3]
	v_pk_mov_b32 v[92:93], v[2:3], v[2:3]
	v_pk_mov_b32 v[94:95], v[2:3], v[2:3]
	v_pk_mov_b32 v[96:97], v[2:3], v[2:3]
	v_pk_mov_b32 v[98:99], v[2:3], v[2:3]
	v_pk_mov_b32 v[100:101], v[2:3], v[2:3]
	v_pk_mov_b32 v[102:103], v[2:3], v[2:3]
	v_pk_mov_b32 v[104:105], v[2:3], v[2:3]
	v_pk_mov_b32 v[106:107], v[2:3], v[2:3]
	v_pk_mov_b32 v[108:109], v[2:3], v[2:3]
	v_pk_mov_b32 v[110:111], v[2:3], v[2:3]
	v_pk_mov_b32 v[112:113], v[2:3], v[2:3]
	v_pk_mov_b32 v[114:115], v[2:3], v[2:3]
	v_pk_mov_b32 v[116:117], v[2:3], v[2:3]
	v_pk_mov_b32 v[118:119], v[2:3], v[2:3]
	v_pk_mov_b32 v[120:121], v[2:3], v[2:3]
	v_pk_mov_b32 v[122:123], v[2:3], v[2:3]
	v_pk_mov_b32 v[124:125], v[2:3], v[2:3]
	v_pk_mov_b32 v[126:127], v[2:3], v[2:3]
	v_pk_mov_b32 v[128:129], v[2:3], v[2:3]
	.p2align	6
